# baseline (speedup 1.0000x reference)
; template <class Epi> ...
;     ...
;   const int wid = cx.tid >> 6, lane = cx.tid & 63, wr = wid >> 2, wc = wid & 3, fr = lane & 15, fq = lane >> 4;
;   const int wv1k = __builtin_amdgcn_readfirstlane(cx.tid >> 6) * 1024;
;   unsigned so0, so1;
;   { int r, c; stage_rc(cx.tid * 16, r, c); so0 = (unsigned)(r * K + c) * 2u; stage_rc(cx.tid * 16 + 8192, r, c); so1 = (unsigned)(r * K + c) * 2u; }
.LBB0_58:
	s_cmp_eq_u32 s28, 1
	s_mov_b64 s[4:5], -1
	s_cbranch_scc0 .LBB0_69
	s_cmpk_gt_i32 s59, 0x20ff
	s_cbranch_scc1 .LBB0_68
	v_ashrrev_i32_e32 v2, 31, v150
	v_lshrrev_b32_e32 v2, 26, v2
	v_add_u32_e32 v4, v150, v2
	v_bfe_i32 v2, v150, 27, 1
	v_lshlrev_b32_e32 v0, 4, v150
	v_lshrrev_b32_e32 v2, 22, v2
	v_add_u32_e32 v2, v0, v2
	v_and_b32_e32 v2, 0xfffffc00, v2
	v_sub_u32_e32 v2, v0, v2
	v_lshrrev_b32_e32 v3, 4, v2
	v_bitop3_b32 v2, v3, v2, 32 bitop3:0x6c
	v_ashrrev_i32_e32 v6, 31, v2
	v_lshrrev_b32_e32 v6, 26, v6
	v_add_u32_e32 v6, v2, v6
	v_ashrrev_i32_e32 v7, 6, v6
	v_and_b32_e32 v6, 0xc0, v6
	v_ashrrev_i32_e32 v5, 6, v4
	v_sub_u32_e32 v2, v2, v6
	v_mov_b32_e32 v13, 1
	v_lshlrev_b32_e32 v8, 5, v5
	v_ashrrev_i16_sdwa v2, v13, sext(v2) dst_sel:DWORD dst_unused:UNUSED_PAD src0_sel:DWORD src1_sel:BYTE_0
	v_and_b32_e32 v8, 32, v8
	v_bfe_i32 v6, v2, 0, 16
	v_add_u32_e32 v0, 0x2000, v0
	v_add_u32_e32 v2, v8, v6
	v_ashrrev_i32_e32 v8, 31, v0
	v_lshrrev_b32_e32 v8, 22, v8
	v_add_u32_e32 v8, v0, v8
	v_ashrrev_i32_e32 v8, 10, v8
	v_mul_i32_i24_e32 v9, 0x400, v8
	v_sub_u32_e32 v0, v0, v9
	v_lshrrev_b32_e32 v9, 4, v0
	v_bitop3_b32 v0, v9, v0, 32 bitop3:0x6c
	v_ashrrev_i32_e32 v10, 31, v0
	v_lshrrev_b32_e32 v10, 26, v10
	v_add_u32_e32 v10, v0, v10
	v_ashrrev_i32_e32 v11, 6, v10
	v_and_b32_e32 v10, 0xc0, v10
	v_readlane_b32 s4, v255, 41
	v_sub_u32_e32 v0, v0, v10
	v_readlane_b32 s5, v255, 42
	v_lshlrev_b32_e32 v3, 3, v5
	v_ashrrev_i16_sdwa v0, v13, sext(v0) dst_sel:DWORD dst_unused:UNUSED_PAD src0_sel:DWORD src1_sel:BYTE_0
	s_mov_b32 s6, s4
	s_ashr_i32 s7, s4, 31
	v_writelane_b32 v255, s4, 41
	v_bfe_i32 v10, v0, 0, 16
	v_and_b32_e32 v0, 0x1ffff0, v3
	v_writelane_b32 v255, s5, 42
	s_lshl_b64 s[4:5], s[6:7], 6
	v_lshlrev_b32_e32 v9, 3, v8
	v_lshlrev_b32_e32 v12, 5, v8
	v_add_lshl_u32 v0, v7, v0, 11
	s_add_u32 s6, s88, s4
	v_and_b32_e32 v12, 32, v12
	v_lshl_add_u32 v0, v2, 1, v0
	v_and_b32_e32 v2, 0x1ffff0, v9
	s_addc_u32 s7, s89, s5
	v_ashrrev_i32_e32 v151, 6, v150
	v_add_u32_e32 v12, v12, v10
	v_add_lshl_u32 v2, v11, v2, 11
	s_and_b64 s[4:5], s[14:15], exec
	v_and_b32_e32 v14, 15, v150
	v_lshl_add_u32 v130, v12, 1, v2
	v_lshlrev_b32_e32 v2, 12, v151
	v_lshlrev_b32_e32 v3, 2, v150
	s_cselect_b32 s4, 48, 0
	v_and_b32_e32 v15, 48, v150
	v_and_b32_e32 v9, 0x3000, v2
	v_lshlrev_b32_e32 v2, 6, v14
	v_and_b32_e32 v3, 32, v3
	s_add_u32 s4, s6, s4
	v_bitop3_b32 v2, v2, v3, v15 bitop3:0x36
	v_readlane_b32 s6, v255, 21
	v_add_u32_e32 v18, 0, v2
	s_addc_u32 s5, s7, 0
	v_add_u32_e32 v12, s6, v2
	v_readlane_b32 s6, v255, 22
	s_load_dwordx4 s[8:11], s[88:89], 0x168
	s_load_dwordx2 s[18:19], s[4:5], 0xb0
	v_add_u32_e32 v14, s6, v2
	v_readlane_b32 s6, v255, 23
	v_lshlrev_b32_e32 v5, 14, v5
	v_and_b32_e32 v5, 0xffff8000, v5
	v_add_u32_e32 v16, s6, v2
	v_readlane_b32 s6, v255, 24
	v_ashrrev_i32_e32 v13, 8, v150
	v_lshl_add_u32 v5, v7, 11, v5
	v_add_u32_e32 v17, s6, v2
	v_lshlrev_b32_e32 v2, 6, v150
	s_movk_i32 s6, 0x3c0
	v_and_or_b32 v2, v2, s6, v15
	v_xad_u32 v15, v2, v3, 0
	v_lshlrev_b32_e32 v2, 14, v8
	v_and_b32_e32 v2, 0xffff8000, v2
	v_lshl_add_u32 v2, v11, 11, v2
	v_lshlrev_b32_e32 v3, 6, v8
	v_cmp_eq_u32_e64 s[4:5], 1, v13
	v_lshlrev_b32_e32 v13, 13, v13
	v_and_or_b32 v2, v3, 64, v2
	v_and_or_b32 v4, v4, 64, v5
	v_or_b32_e32 v19, 0x800, v13
	v_or_b32_e32 v20, 0x1000, v13
	v_or_b32_e32 v21, 0x1800, v13
	s_movk_i32 s6, 0x100
	v_lshl_add_u32 v2, v10, 1, v2
	v_mov_b32_e32 v3, v1
	v_lshl_add_u32 v4, v6, 1, v4
	v_mov_b32_e32 v5, v1
	v_mov_b32_e32 v131, v1
	v_cmp_gt_u32_e64 s[6:7], s6, v150
	s_waitcnt lgkmcnt(0)
	v_lshl_add_u64 v[132:133], s[8:9], 0, v[2:3]
	v_lshl_add_u64 v[134:135], s[8:9], 0, v[4:5]
	v_lshl_add_u64 v[136:137], s[18:19], 0, v[2:3]
	v_lshl_add_u64 v[138:139], s[18:19], 0, v[4:5]
	v_add_u32_e32 v154, v12, v9
	v_add_u32_e32 v155, v18, v13
	v_add_u32_e32 v156, v15, v19
	v_add_u32_e32 v157, v15, v20
	v_add_u32_e32 v158, v15, v21
	v_add_u32_e32 v159, v14, v9
	v_add_u32_e32 v160, v16, v9
	v_add_u32_e32 v161, v17, v9
	v_readfirstlane_b32 s20, v150
	s_nop 3
	s_lshr_b32 s20, s20, 6
	s_cmp_ge_u32 s20, 4
	s_cbranch_scc1 .Lprio_g1_done
.Lprio_g1_done:
	s_mov_b32 s29, s59
	s_branch .LBB0_62

; DEVINL bool run_phase(int ph, int rep) {
;     ...
;       for (int t = cx.bid; t < nwg; t += cx.nb) {
;         int pm, pn; tile_coords(t, nM, nN, pm, pn);
;         const int grow = pm * BM;
;         const float* res = fx ? x_row(p, grow) - (size_t)grow * DM : p.out;
;         EpiRes e{res, p.out, p.mod + (size_t)seq_of_row(grow) * (2 * MODW) + l * MODW + (f2 ? 8 : 2) * DM, 0.5f};
.LBB0_74:
	v_readfirstlane_b32 s100, v234
	s_nop 3
	s_lshr_b32 s100, s100, 6
	s_cmp_ge_u32 s100, 4
	s_cbranch_scc1 .Lprio_74_done
.Lprio_74_done:
	s_and_b32 s24, s40, 7
	s_ashr_i32 s18, s40, 3
	s_mul_i32 s19, s24, 0xc0
	s_add_i32 s18, s19, s18
	s_ashr_i32 s19, s18, 31
	s_lshr_b32 s19, s19, 27
	s_add_i32 s19, s18, s19
	s_and_b32 s20, s19, 0xffe0
	s_sub_i32 s18, s18, s20
	s_bfe_i32 s20, s18, 0x80000
	s_bfe_u32 s20, s20, 0x3000c
	s_add_i32 s26, s18, s20
	s_and_b32 s20, s26, 0xf8
	s_sub_i32 s18, s18, s20
	s_sext_i32_i8 s18, s18
	s_lshl_b32 s19, s19, 6
	s_and_b32 s19, s19, 0xfffff800
	s_lshl_b32 s18, s18, 8
	s_andn2_b64 vcc, exec, s[16:17]
	s_add_i32 s18, s18, s19
	s_cbranch_vccnz .LBB0_76
	s_load_dwordx4 s[20:23], s[88:89], 0x0
	s_add_i32 s25, s18, 0xffff0000
	s_ashr_i32 s19, s18, 31
	s_cmp_lt_i32 s18, 0x10000
	s_cselect_b32 s29, s19, 0
	s_cselect_b32 s28, s18, s25
	s_waitcnt lgkmcnt(0)
	s_cselect_b32 s23, s21, s23
	s_cselect_b32 s22, s20, s22
	s_lshl_b64 s[20:21], s[28:29], 12
	s_add_u32 s22, s22, s20
	s_addc_u32 s23, s23, s21
	s_lshl_b64 s[20:21], s[18:19], 12
	s_sub_u32 s20, 0, s20
	s_subb_u32 s21, 0, s21
	s_add_u32 s22, s22, s20
	s_addc_u32 s23, s23, s21
	s_mov_b64 s[20:21], 0
	s_branch .LBB0_77

;   DEVINL float4 gate(int c0) const {
;     float4 g4 = *(const float4*)(g + c0);
;     g4.x *= gs; g4.y *= gs; g4.z *= gs; g4.w *= gs;
;     g4.x = fabsf(g4.x) > 1e-20f ? g4.x : 1e-20f; g4.y = fabsf(g4.y) > 1e-20f ? g4.y : 1e-20f;
;     g4.z = fabsf(g4.z) > 1e-20f ? g4.z : 1e-20f; g4.w = fabsf(g4.w) > 1e-20f ? g4.w : 1e-20f;
;     return g4;
;   }
;   DEVINL void init(Acc& acc, int brow, int bcol) const {
;     EPI_IDS
;     const int c0 = bcol + wc * 64 + fr * 4;
;     const float4 g4 = gate(c0);
;     float4 iv; iv.x = 1.f / g4.x; iv.y = 1.f / g4.y; iv.z = 1.f / g4.z; iv.w = 1.f / g4.w;
;     _Pragma("unroll") for (int ai = 0; ai < 2; ++ai) _Pragma("unroll") for (int m = 0; m < 4; ++m) {
;       _Pragma("unroll") for (int j = 0; j < 4; ++j) {
;         const int row = brow + ai * 128 + wr * 64 + m * 16 + fq * 4 + j;
;         const float4 r = *(const float4*)(res + (size_t)row * DM + c0);
;         acc[ai][0][m][0][j] = r.x * iv.x; acc[ai][0][m][1][j] = r.y * iv.y; acc[ai][1][m][0][j] = r.z * iv.z; acc[ai][1][m][1][j] = r.w * iv.w;
;       }
; DEVINL bool run_phase(int ph, int rep) {
;     ...
;       for (int t = cx.bid; t < nwg; t += cx.nb) {
;         int pm, pn; tile_coords(t, nM, nN, pm, pn);
;         const int s = gi.sbase + (pm * BM) / gi.L;
;         EpiRes e{hout, hout, p.mod + (size_t)s * (2 * MODW) + l * MODW + 5 * DM, 1.0f};
;         Acc acc; e.init(acc, pm * BM, pn * BM);
.LBB0_112:
	v_readfirstlane_b32 s100, v234
	s_nop 3
	s_lshr_b32 s100, s100, 6
	s_cmp_ge_u32 s100, 4
	s_cbranch_scc1 .Lprio_112_done
.Lprio_112_done:
	s_and_b32 s16, s41, 7
	s_ashr_i32 s17, s41, 3
	s_mul_i32 s18, s16, s37
	s_add_i32 s17, s18, s17
	s_ashr_i32 s18, s17, 31
	s_lshr_b32 s18, s18, 27
	s_add_i32 s18, s17, s18
	s_ashr_i32 s19, s18, 5
	s_lshl_b32 s19, s19, 3
	s_sub_i32 s20, s35, s19
	s_min_i32 s20, s20, 8
	s_abs_i32 s21, s20
	v_cvt_f32_u32_e32 v2, s21
	s_sub_i32 s23, 0, s21
	s_andn2_b32 s18, s18, 31
	s_sub_i32 s17, s17, s18
	v_rcp_iflag_f32_e32 v2, v2
	s_abs_i32 s18, s17
	s_xor_b32 s22, s17, s20
	s_ashr_i32 s22, s22, 31
	v_mul_f32_e32 v2, 0x4f7ffffe, v2
	v_cvt_u32_f32_e32 v2, v2
	s_mul_i32 s16, s16, 3
	v_mov_b32_e32 v8, v234
	v_readfirstlane_b32 s24, v2
	s_mul_i32 s23, s23, s24
	s_mul_hi_u32 s23, s24, s23
	s_add_i32 s24, s24, s23
	s_mul_hi_u32 s23, s18, s24
	s_mul_i32 s24, s23, s21
	s_sub_i32 s18, s18, s24
	s_add_i32 s25, s23, 1
	s_sub_i32 s24, s18, s21
	s_cmp_ge_u32 s18, s21
	s_cselect_b32 s23, s25, s23
	s_cselect_b32 s18, s24, s18
	s_add_i32 s24, s23, 1
	s_cmp_ge_u32 s18, s21
	s_cselect_b32 s18, s24, s23
	s_xor_b32 s18, s18, s22
	s_sub_i32 s18, s18, s22
	s_mul_i32 s20, s18, s20
	s_sub_i32 s17, s17, s20
	s_add_i32 s16, s18, s16
	s_add_i32 s19, s19, s17
	s_bfe_i32 s17, s16, 0x80000
	s_bfe_u32 s17, s17, 0x2000d
	s_add_i32 s17, s16, s17
	s_and_b32 s17, s17, 0xfc
	s_sub_i32 s16, s16, s17
	s_sext_i32_i8 s20, s16
	s_lshl_b32 s16, s19, 8
	s_abs_i32 s18, s16
	s_mul_hi_u32 s19, s18, s40
	s_mul_i32 s21, s19, s62
	s_sub_i32 s18, s18, s21
	s_ashr_i32 s17, s16, 31
	s_add_i32 s21, s19, 1
	s_sub_i32 s22, s18, s62
	s_cmp_ge_u32 s18, s62
	s_cselect_b32 s19, s21, s19
	s_cselect_b32 s18, s22, s18
	s_add_i32 s21, s19, 1
	s_cmp_ge_u32 s18, s62
	s_cselect_b32 s18, s21, s19
	s_xor_b32 s18, s18, s17
	s_sub_i32 s18, s18, s17
	s_add_i32 s18, s18, s34
	s_mul_hi_i32 s19, s18, 0x12000
	s_mul_i32 s18, s18, 0x12000
	v_ashrrev_i32_e32 v9, 2, v8
	s_add_u32 s18, s38, s18
	v_and_b32_e32 v9, 0xffffffc0, v9
	s_addc_u32 s19, s39, s19
	v_and_b32_e32 v2, 0xc0, v8
	v_lshlrev_b32_e32 v3, 2, v8
	v_lshrrev_b32_e32 v8, 2, v8
	v_add_u32_e32 v9, s16, v9
	s_add_u32 s18, s18, 0x5000
	v_and_or_b32 v8, v8, 12, v9
	s_addc_u32 s19, s19, 0
	s_lshl_b32 s20, s20, 8
	v_and_b32_e32 v3, 60, v3
	v_or_b32_e32 v12, 1, v8
	v_or3_b32 v2, v3, v2, s20
	v_ashrrev_i32_e32 v9, 31, v8
	v_ashrrev_i32_e32 v13, 31, v12
	v_ashrrev_i32_e32 v3, 31, v2
	v_lshlrev_b64 v[10:11], 12, v[8:9]
	v_lshlrev_b64 v[12:13], 12, v[12:13]
	v_lshlrev_b64 v[6:7], 2, v[2:3]
	v_lshl_add_u64 v[10:11], s[12:13], 0, v[10:11]
	v_lshl_add_u64 v[12:13], s[12:13], 0, v[12:13]
	v_lshl_add_u64 v[2:3], s[18:19], 0, v[6:7]
	v_lshl_add_u64 v[10:11], v[10:11], 0, v[6:7]
	v_lshl_add_u64 v[12:13], v[12:13], 0, v[6:7]
	global_load_dwordx4 v[2:5], v[2:3], off
	s_nop 0
	global_load_dwordx4 v[20:23], v[10:11], off
	global_load_dwordx4 v[16:19], v[12:13], off
	v_or_b32_e32 v10, 2, v8
	v_or_b32_e32 v12, 3, v8
	v_ashrrev_i32_e32 v11, 31, v10
	v_ashrrev_i32_e32 v13, 31, v12
	v_lshlrev_b64 v[10:11], 12, v[10:11]
	v_lshlrev_b64 v[12:13], 12, v[12:13]
	v_lshl_add_u64 v[10:11], s[12:13], 0, v[10:11]
	v_lshl_add_u64 v[12:13], s[12:13], 0, v[12:13]
	v_lshl_add_u64 v[10:11], v[10:11], 0, v[6:7]
	v_lshl_add_u64 v[12:13], v[12:13], 0, v[6:7]
	global_load_dwordx4 v[30:33], v[10:11], off
	s_nop 0
	global_load_dwordx4 v[12:15], v[12:13], off
	v_or_b32_e32 v10, 16, v8
	v_ashrrev_i32_e32 v11, 31, v10
	v_or_b32_e32 v24, 17, v8
	v_lshlrev_b64 v[10:11], 12, v[10:11]
	v_ashrrev_i32_e32 v25, 31, v24
	v_lshl_add_u64 v[10:11], s[12:13], 0, v[10:11]
	v_lshlrev_b64 v[24:25], 12, v[24:25]
	v_lshl_add_u64 v[10:11], v[10:11], 0, v[6:7]
	v_lshl_add_u64 v[24:25], s[12:13], 0, v[24:25]
	v_lshl_add_u64 v[24:25], v[24:25], 0, v[6:7]
	global_load_dwordx4 v[62:65], v[10:11], off
	global_load_dwordx4 v[58:61], v[24:25], off
	v_or_b32_e32 v10, 18, v8
	v_ashrrev_i32_e32 v11, 31, v10
	v_or_b32_e32 v24, 19, v8
	v_lshlrev_b64 v[10:11], 12, v[10:11]
	v_ashrrev_i32_e32 v25, 31, v24
	v_lshl_add_u64 v[10:11], s[12:13], 0, v[10:11]
	v_lshlrev_b64 v[24:25], 12, v[24:25]
	v_lshl_add_u64 v[10:11], v[10:11], 0, v[6:7]
	v_lshl_add_u64 v[24:25], s[12:13], 0, v[24:25]
	v_lshl_add_u64 v[24:25], v[24:25], 0, v[6:7]
	global_load_dwordx4 v[86:89], v[10:11], off
	global_load_dwordx4 v[26:29], v[24:25], off
	v_or_b32_e32 v10, 32, v8
	v_ashrrev_i32_e32 v11, 31, v10
	v_or_b32_e32 v24, 33, v8
	v_lshlrev_b64 v[10:11], 12, v[10:11]
	v_ashrrev_i32_e32 v25, 31, v24
	v_lshl_add_u64 v[10:11], s[12:13], 0, v[10:11]
	v_lshlrev_b64 v[24:25], 12, v[24:25]
	v_lshl_add_u64 v[10:11], v[10:11], 0, v[6:7]
	v_lshl_add_u64 v[24:25], s[12:13], 0, v[24:25]
	v_lshl_add_u64 v[24:25], v[24:25], 0, v[6:7]
	global_load_dwordx4 v[118:121], v[10:11], off
	global_load_dwordx4 v[114:117], v[24:25], off
	v_or_b32_e32 v10, 34, v8
	v_ashrrev_i32_e32 v11, 31, v10
	v_or_b32_e32 v24, 35, v8
	v_lshlrev_b64 v[10:11], 12, v[10:11]
	v_ashrrev_i32_e32 v25, 31, v24
	v_lshl_add_u64 v[10:11], s[12:13], 0, v[10:11]
	v_lshlrev_b64 v[24:25], 12, v[24:25]
	v_lshl_add_u64 v[10:11], v[10:11], 0, v[6:7]
	v_lshl_add_u64 v[24:25], s[12:13], 0, v[24:25]
	v_lshl_add_u64 v[24:25], v[24:25], 0, v[6:7]
	global_load_dwordx4 v[130:133], v[10:11], off
	global_load_dwordx4 v[82:85], v[24:25], off
	v_or_b32_e32 v10, 48, v8
	v_ashrrev_i32_e32 v11, 31, v10
	v_or_b32_e32 v24, 49, v8
	v_lshlrev_b64 v[10:11], 12, v[10:11]
	v_ashrrev_i32_e32 v25, 31, v24
	v_lshl_add_u64 v[10:11], s[12:13], 0, v[10:11]
	v_lshlrev_b64 v[24:25], 12, v[24:25]
	v_lshl_add_u64 v[10:11], v[10:11], 0, v[6:7]
	v_lshl_add_u64 v[24:25], s[12:13], 0, v[24:25]
	v_lshl_add_u64 v[24:25], v[24:25], 0, v[6:7]
; #define STAGE(P, BASE, br, kt) do { const char* _gb = (const char*)((BASE) + ((long)(br) * K + (long)(kt) * BK)); \
;     __builtin_amdgcn_global_load_lds((const unsigned*)(_gb + (size_t)so0), (unsigned*)((char*)(P) + wv1k), 16, 0, 0); \
;     __builtin_amdgcn_global_load_lds((const unsigned*)(_gb + (size_t)so1), (unsigned*)((char*)(P) + wv1k + 8192), 16, 0, 0); } while (0)
; #define BAR __builtin_amdgcn_s_barrier()
; template <class Epi> ...
;     ...
;   const int wv1k = __builtin_amdgcn_readfirstlane(cx.tid >> 6) * 1024;
;   unsigned so0, so1;
;   { int r, c; stage_rc(cx.tid * 16, r, c); so0 = (unsigned)(r * K + c) * 2u; stage_rc(cx.tid * 16 + 8192, r, c); so1 = (unsigned)(r * K + c) * 2u; }
;   if (zinit) {
;     _Pragma("unroll") for (int ai = 0; ai < 2; ++ai) _Pragma("unroll") for (int bj = 0; bj < 2; ++bj) _Pragma("unroll") for (int m = 0; m < 4; ++m) _Pragma("unroll") for (int n = 0; n < 2; ++n) acc[ai][bj][m][n] = f32x4{0.f, 0.f, 0.f, 0.f};
;   }
;   bf16x8 At[4][2], B0[2][2], B1[2][2];
;   const int nt = K / BK;
;   if (!(OVERLAP && pre)) {
;     STAGE(SB(0, 0), Bt, bcol, 0); STAGE(SA(0, 0), A, brow, 0);
;     STAGE(SB(0, 1), Bt, bcol + HALF, 0); STAGE(SA(0, 1), A, brow + HALF, 0);
;   }
;   if (wr == 1) BAR;
;   DEVINL void init(Acc& acc, int brow, int bcol) const {
;     ...
;     _Pragma("unroll") for (int ai = 0; ai < 2; ++ai) _Pragma("unroll") for (int m = 0; m < 4; ++m) {
;       _Pragma("unroll") for (int j = 0; j < 4; ++j) {
;         const int row = brow + ai * 128 + wr * 64 + m * 16 + fq * 4 + j;
;         const float4 r = *(const float4*)(res + (size_t)row * DM + c0);
;         acc[ai][0][m][0][j] = r.x * iv.x; acc[ai][0][m][1][j] = r.y * iv.y; acc[ai][1][m][0][j] = r.z * iv.z; acc[ai][1][m][1][j] = r.w * iv.w;
;       }
	global_load_dwordx4 v[134:137], v[10:11], off
	global_load_dwordx4 v[122:125], v[24:25], off
	v_or_b32_e32 v10, 50, v8
	v_ashrrev_i32_e32 v11, 31, v10
	v_or_b32_e32 v24, 51, v8
	v_lshlrev_b64 v[10:11], 12, v[10:11]
	v_ashrrev_i32_e32 v25, 31, v24
	v_lshl_add_u64 v[10:11], s[12:13], 0, v[10:11]
	v_lshlrev_b64 v[24:25], 12, v[24:25]
	v_lshl_add_u64 v[10:11], v[10:11], 0, v[6:7]
	v_lshl_add_u64 v[24:25], s[12:13], 0, v[24:25]
	v_lshl_add_u64 v[24:25], v[24:25], 0, v[6:7]
	global_load_dwordx4 v[138:141], v[10:11], off
	global_load_dwordx4 v[126:129], v[24:25], off
	v_add_u32_e32 v10, 0x80, v8
	v_ashrrev_i32_e32 v11, 31, v10
	v_add_u32_e32 v24, 0x81, v8
	v_lshlrev_b64 v[10:11], 12, v[10:11]
	v_ashrrev_i32_e32 v25, 31, v24
	v_lshl_add_u64 v[10:11], s[12:13], 0, v[10:11]
	v_lshlrev_b64 v[24:25], 12, v[24:25]
	v_lshl_add_u64 v[10:11], v[10:11], 0, v[6:7]
	v_lshl_add_u64 v[24:25], s[12:13], 0, v[24:25]
	v_lshl_add_u64 v[24:25], v[24:25], 0, v[6:7]
	global_load_dwordx4 v[34:37], v[10:11], off
	global_load_dwordx4 v[38:41], v[24:25], off
	v_add_u32_e32 v10, 0x82, v8
	v_ashrrev_i32_e32 v11, 31, v10
	v_add_u32_e32 v24, 0x83, v8
	v_lshlrev_b64 v[10:11], 12, v[10:11]
	v_ashrrev_i32_e32 v25, 31, v24
	v_lshl_add_u64 v[10:11], s[12:13], 0, v[10:11]
	v_lshlrev_b64 v[24:25], 12, v[24:25]
	v_lshl_add_u64 v[10:11], v[10:11], 0, v[6:7]
	v_lshl_add_u64 v[24:25], s[12:13], 0, v[24:25]
	v_lshl_add_u64 v[24:25], v[24:25], 0, v[6:7]
	global_load_dwordx4 v[50:53], v[10:11], off
	global_load_dwordx4 v[54:57], v[24:25], off
	v_add_u32_e32 v10, 0x90, v8
	v_ashrrev_i32_e32 v11, 31, v10
	v_add_u32_e32 v24, 0x91, v8
	v_lshlrev_b64 v[10:11], 12, v[10:11]
	v_ashrrev_i32_e32 v25, 31, v24
	v_lshl_add_u64 v[10:11], s[12:13], 0, v[10:11]
	v_lshlrev_b64 v[24:25], 12, v[24:25]
	v_lshl_add_u64 v[10:11], v[10:11], 0, v[6:7]
	v_lshl_add_u64 v[24:25], s[12:13], 0, v[24:25]
	v_lshl_add_u64 v[24:25], v[24:25], 0, v[6:7]
	global_load_dwordx4 v[42:45], v[10:11], off
	global_load_dwordx4 v[46:49], v[24:25], off
	v_add_u32_e32 v10, 0x92, v8
	v_ashrrev_i32_e32 v11, 31, v10
	v_add_u32_e32 v24, 0x93, v8
	v_lshlrev_b64 v[10:11], 12, v[10:11]
	v_ashrrev_i32_e32 v25, 31, v24
	v_lshl_add_u64 v[10:11], s[12:13], 0, v[10:11]
	v_lshlrev_b64 v[24:25], 12, v[24:25]
	v_lshl_add_u64 v[10:11], v[10:11], 0, v[6:7]
	v_lshl_add_u64 v[24:25], s[12:13], 0, v[24:25]
	v_lshl_add_u64 v[24:25], v[24:25], 0, v[6:7]
	global_load_dwordx4 v[74:77], v[10:11], off
	global_load_dwordx4 v[78:81], v[24:25], off
	v_add_u32_e32 v10, 0xa0, v8
	v_ashrrev_i32_e32 v11, 31, v10
	v_add_u32_e32 v24, 0xa1, v8
	v_lshlrev_b64 v[10:11], 12, v[10:11]
	v_ashrrev_i32_e32 v25, 31, v24
	v_lshl_add_u64 v[10:11], s[12:13], 0, v[10:11]
	v_lshlrev_b64 v[24:25], 12, v[24:25]
	v_lshl_add_u64 v[10:11], v[10:11], 0, v[6:7]
	v_lshl_add_u64 v[24:25], s[12:13], 0, v[24:25]
	v_lshl_add_u64 v[24:25], v[24:25], 0, v[6:7]
	global_load_dwordx4 v[66:69], v[10:11], off
	global_load_dwordx4 v[70:73], v[24:25], off
	v_add_u32_e32 v10, 0xa2, v8
	v_ashrrev_i32_e32 v11, 31, v10
	v_add_u32_e32 v24, 0xa3, v8
	v_lshlrev_b64 v[10:11], 12, v[10:11]
	v_ashrrev_i32_e32 v25, 31, v24
	v_lshl_add_u64 v[10:11], s[12:13], 0, v[10:11]
	v_lshlrev_b64 v[24:25], 12, v[24:25]
	v_lshl_add_u64 v[10:11], v[10:11], 0, v[6:7]
	v_lshl_add_u64 v[24:25], s[12:13], 0, v[24:25]
	v_lshl_add_u64 v[24:25], v[24:25], 0, v[6:7]
	global_load_dwordx4 v[98:101], v[10:11], off
	global_load_dwordx4 v[102:105], v[24:25], off
	v_add_u32_e32 v10, 0xb0, v8
	v_ashrrev_i32_e32 v11, 31, v10
	v_add_u32_e32 v24, 0xb1, v8
	v_lshlrev_b64 v[10:11], 12, v[10:11]
	v_ashrrev_i32_e32 v25, 31, v24
	v_lshl_add_u64 v[10:11], s[12:13], 0, v[10:11]
	v_lshlrev_b64 v[24:25], 12, v[24:25]
	v_lshl_add_u64 v[10:11], v[10:11], 0, v[6:7]
	v_lshl_add_u64 v[24:25], s[12:13], 0, v[24:25]
	v_lshl_add_u64 v[24:25], v[24:25], 0, v[6:7]
	global_load_dwordx4 v[90:93], v[10:11], off
	global_load_dwordx4 v[94:97], v[24:25], off
	v_add_u32_e32 v10, 0xb2, v8
	v_ashrrev_i32_e32 v11, 31, v10
	v_add_u32_e32 v8, 0xb3, v8
	v_lshlrev_b64 v[10:11], 12, v[10:11]
	v_ashrrev_i32_e32 v9, 31, v8
	v_lshl_add_u64 v[10:11], s[12:13], 0, v[10:11]
	v_lshlrev_b64 v[8:9], 12, v[8:9]
	v_lshl_add_u64 v[10:11], v[10:11], 0, v[6:7]
	v_lshl_add_u64 v[8:9], s[12:13], 0, v[8:9]
	v_lshl_add_u64 v[6:7], v[8:9], 0, v[6:7]
	global_load_dwordx4 v[106:109], v[10:11], off
	global_load_dwordx4 v[110:113], v[6:7], off
	s_load_dwordx2 s[22:23], s[88:89], 0x200
	s_load_dwordx2 s[24:25], s[14:15], 0xd8
	v_readfirstlane_b32 s21, v151
	s_lshl_b32 s30, s21, 10
	s_ashr_i32 s21, s20, 31
	s_lshl_b64 s[26:27], s[20:21], 11
	s_waitcnt lgkmcnt(0)
	s_add_u32 s28, s24, s26
	s_addc_u32 s29, s25, s27
	s_add_i32 s21, s30, 0
	v_lshl_add_u64 v[142:143], s[28:29], 0, v[0:1]
	s_add_i32 s42, s21, 0x10000
	v_lshl_add_u64 v[144:145], s[28:29], 0, v[152:153]
	s_add_i32 s43, s21, 0x12000
	s_lshl_b64 s[28:29], s[16:17], 11
	s_add_u32 s30, s22, s28
	s_addc_u32 s31, s23, s29
	v_lshl_add_u64 v[148:149], s[30:31], 0, v[0:1]
	v_lshl_add_u64 v[146:147], s[30:31], 0, v[152:153]
	s_or_b32 s30, s20, 0x80
	s_ashr_i32 s31, s30, 31
	s_add_i32 s17, s21, 0x2000
	s_lshl_b64 s[30:31], s[30:31], 11
	s_add_u32 s30, s24, s30
	s_mov_b32 m0, s42
	s_addc_u32 s31, s25, s31
	global_load_lds_dwordx4 v[142:143], off
	s_mov_b32 m0, s43
	v_lshl_add_u64 v[166:167], s[30:31], 0, v[0:1]
	v_lshl_add_u64 v[162:163], s[30:31], 0, v[152:153]
	s_or_b32 s30, s16, 0x80
	global_load_lds_dwordx4 v[144:145], off
	s_mov_b32 m0, s21
	s_ashr_i32 s31, s30, 31
	global_load_lds_dwordx4 v[148:149], off
	s_mov_b32 m0, s17
	s_add_i32 s44, s21, 0x14000
	s_add_i32 s45, s21, 0x16000
	s_lshl_b64 s[30:31], s[30:31], 11
	global_load_lds_dwordx4 v[146:147], off
	s_mov_b32 m0, s44
	s_add_u32 s30, s22, s30
	global_load_lds_dwordx4 v[166:167], off
	s_mov_b32 m0, s45
	s_addc_u32 s31, s23, s31
	s_add_i32 s46, s21, 0x4000
	global_load_lds_dwordx4 v[162:163], off
	v_lshl_add_u64 v[158:159], s[30:31], 0, v[0:1]
	s_mov_b32 m0, s46
	s_add_i32 s47, s21, 0x6000
	global_load_lds_dwordx4 v[158:159], off
	v_lshl_add_u64 v[160:161], s[30:31], 0, v[152:153]
	s_mov_b32 m0, s47
	s_nop 0
	global_load_lds_dwordx4 v[160:161], off
	s_and_saveexec_b64 s[30:31], s[4:5]
	s_cbranch_execz .LBB0_114
	s_barrier

; template <class Epi> ...
;     ...
;   if (zinit) {
;     _Pragma("unroll") for (int ai = 0; ai < 2; ++ai) _Pragma("unroll") for (int bj = 0; bj < 2; ++bj) _Pragma("unroll") for (int m = 0; m < 4; ++m) _Pragma("unroll") for (int n = 0; n < 2; ++n) acc[ai][bj][m][n] = f32x4{0.f, 0.f, 0.f, 0.f};
;   }
; DEVINL bool run_phase(int ph, int rep) {
;     ...
;       for (int v = 0; v < 2 * ntl; ++v) {
;         const int t = cx.bid + (v >> 1) * cx.nb, which = v & 1;
;         int pm, pn; tile_coords(t, nM, nN, pm, pn);
;         EpiMix e{p.sgr, p.sgn, p.merged, which};
;         gemm_tile_acc(acc, which == 0, cx, which ? p.nao : p.y, p.wt[l][which ? 4 : 3], which ? 512 : DM, pm * BM, pn * BM, e, false, nullptr, nullptr, 0, -1, 0);
.LBB0_128:
	v_readfirstlane_b32 s100, v234
	s_nop 3
	s_lshr_b32 s100, s100, 6
	s_cmp_ge_u32 s100, 4
	s_cbranch_scc1 .Lprio_128_done
.Lprio_128_done:
	s_and_b32 s9, s54, 1
	s_bitcmp1_b32 s54, 0
	s_cselect_b64 s[18:19], -1, 0
	s_cmp_eq_u32 s9, 0
	s_cselect_b64 s[28:29], -1, 0
	s_and_b64 s[20:21], s[28:29], exec
	s_movk_i32 s8, 0x1f0
	s_cselect_b32 s8, s8, 0x1f8
	s_add_u32 s20, s88, s8
	s_addc_u32 s21, s89, 0
	s_lshl_b32 s8, s9, 3
	s_load_dwordx2 s[24:25], s[20:21], 0x0
	s_load_dwordx2 s[26:27], s[16:17], s8 offset:0xc8
	v_readfirstlane_b32 s21, v148
	s_and_b64 vcc, exec, s[18:19]
	s_cbranch_vccnz .LBB0_130
	v_mov_b32_e32 v2, v1
	v_mov_b32_e32 v3, v1
	v_mov_b32_e32 v0, v1
	v_mov_b64_e32 v[30:31], v[2:3]
	v_mov_b64_e32 v[34:35], v[2:3]
	v_mov_b64_e32 v[22:23], v[2:3]
	v_mov_b64_e32 v[26:27], v[2:3]
	v_mov_b64_e32 v[14:15], v[2:3]
	v_mov_b64_e32 v[18:19], v[2:3]
	v_mov_b64_e32 v[6:7], v[2:3]
	v_mov_b64_e32 v[10:11], v[2:3]
	v_mov_b64_e32 v[62:63], v[2:3]
	v_mov_b64_e32 v[66:67], v[2:3]
	v_mov_b64_e32 v[54:55], v[2:3]
	v_mov_b64_e32 v[58:59], v[2:3]
	v_mov_b64_e32 v[46:47], v[2:3]
	v_mov_b64_e32 v[50:51], v[2:3]
	v_mov_b64_e32 v[38:39], v[2:3]
	v_mov_b64_e32 v[42:43], v[2:3]
	v_mov_b64_e32 v[94:95], v[2:3]
	v_mov_b64_e32 v[98:99], v[2:3]
	v_mov_b64_e32 v[86:87], v[2:3]
	v_mov_b64_e32 v[90:91], v[2:3]
	v_mov_b64_e32 v[78:79], v[2:3]
	v_mov_b64_e32 v[82:83], v[2:3]
	v_mov_b64_e32 v[70:71], v[2:3]
	v_mov_b64_e32 v[74:75], v[2:3]
	v_mov_b64_e32 v[126:127], v[2:3]
	v_mov_b64_e32 v[130:131], v[2:3]
	v_mov_b64_e32 v[118:119], v[2:3]
	v_mov_b64_e32 v[122:123], v[2:3]
	v_mov_b64_e32 v[110:111], v[2:3]
	v_mov_b64_e32 v[114:115], v[2:3]
	v_mov_b64_e32 v[102:103], v[2:3]
	v_mov_b64_e32 v[106:107], v[2:3]
	v_mov_b64_e32 v[28:29], v[0:1]
	v_mov_b64_e32 v[32:33], v[0:1]
	v_mov_b64_e32 v[20:21], v[0:1]
	v_mov_b64_e32 v[24:25], v[0:1]
	v_mov_b64_e32 v[12:13], v[0:1]
	v_mov_b64_e32 v[16:17], v[0:1]
	v_mov_b64_e32 v[4:5], v[0:1]
	v_mov_b64_e32 v[8:9], v[0:1]
	v_mov_b64_e32 v[60:61], v[0:1]
	v_mov_b64_e32 v[64:65], v[0:1]
	v_mov_b64_e32 v[52:53], v[0:1]
	v_mov_b64_e32 v[56:57], v[0:1]
	v_mov_b64_e32 v[44:45], v[0:1]
	v_mov_b64_e32 v[48:49], v[0:1]
	v_mov_b64_e32 v[36:37], v[0:1]
	v_mov_b64_e32 v[40:41], v[0:1]
	v_mov_b64_e32 v[92:93], v[0:1]
	v_mov_b64_e32 v[96:97], v[0:1]
	v_mov_b64_e32 v[84:85], v[0:1]
	v_mov_b64_e32 v[88:89], v[0:1]
	v_mov_b64_e32 v[76:77], v[0:1]
	v_mov_b64_e32 v[80:81], v[0:1]
	v_mov_b64_e32 v[68:69], v[0:1]
	v_mov_b64_e32 v[72:73], v[0:1]
	v_mov_b64_e32 v[124:125], v[0:1]
	v_mov_b64_e32 v[128:129], v[0:1]
	v_mov_b64_e32 v[116:117], v[0:1]
	v_mov_b64_e32 v[120:121], v[0:1]
	v_mov_b64_e32 v[108:109], v[0:1]
	v_mov_b64_e32 v[112:113], v[0:1]
	v_mov_b64_e32 v[100:101], v[0:1]
	v_mov_b64_e32 v[104:105], v[0:1]

; #define STAGE(P, BASE, br, kt) do { const char* _gb = (const char*)((BASE) + ((long)(br) * K + (long)(kt) * BK)); \
;     __builtin_amdgcn_global_load_lds((const unsigned*)(_gb + (size_t)so0), (unsigned*)((char*)(P) + wv1k), 16, 0, 0); \
;     __builtin_amdgcn_global_load_lds((const unsigned*)(_gb + (size_t)so1), (unsigned*)((char*)(P) + wv1k + 8192), 16, 0, 0); } while (0)
; #define BAR __builtin_amdgcn_s_barrier()
; template <class Epi> ...
;     ...
;   const int wv1k = __builtin_amdgcn_readfirstlane(cx.tid >> 6) * 1024;
;   unsigned so0, so1;
;   { int r, c; stage_rc(cx.tid * 16, r, c); so0 = (unsigned)(r * K + c) * 2u; stage_rc(cx.tid * 16 + 8192, r, c); so1 = (unsigned)(r * K + c) * 2u; }
;   if (zinit) {
;     _Pragma("unroll") for (int ai = 0; ai < 2; ++ai) _Pragma("unroll") for (int bj = 0; bj < 2; ++bj) _Pragma("unroll") for (int m = 0; m < 4; ++m) _Pragma("unroll") for (int n = 0; n < 2; ++n) acc[ai][bj][m][n] = f32x4{0.f, 0.f, 0.f, 0.f};
;   }
;   bf16x8 At[4][2], B0[2][2], B1[2][2];
;   const int nt = K / BK;
;   if (!(OVERLAP && pre)) {
;     STAGE(SB(0, 0), Bt, bcol, 0); STAGE(SA(0, 0), A, brow, 0);
;     STAGE(SB(0, 1), Bt, bcol + HALF, 0); STAGE(SA(0, 1), A, brow + HALF, 0);
;   }
;   if (wr == 1) BAR;
.LBB0_446:
	v_readfirstlane_b32 s100, v234
	s_nop 3
	s_lshr_b32 s100, s100, 6
	s_cmp_ge_u32 s100, 4
	s_cbranch_scc1 .Lprio_446_done
.Lprio_446_done:
	s_and_b32 s8, s36, 7
	s_ashr_i32 s9, s36, 3
	s_mul_i32 s10, s8, s34
	s_add_i32 s10, s10, s9
	s_mul_hi_i32 s9, s10, 0x4ec4ec4f
	s_lshr_b32 s11, s9, 31
	s_ashr_i32 s9, s9, 6
	s_add_i32 s9, s9, s11
	s_lshl_b32 s11, s9, 3
	s_sub_i32 s12, s30, s11
	s_min_i32 s12, s12, 8
	s_abs_i32 s13, s12
	v_cvt_f32_u32_e32 v0, s13
	s_sub_i32 s15, 0, s13
	s_mulk_i32 s9, 0xd0
	s_sub_i32 s9, s10, s9
	v_rcp_iflag_f32_e32 v0, v0
	s_abs_i32 s10, s9
	s_xor_b32 s14, s9, s12
	s_ashr_i32 s14, s14, 31
	v_mul_f32_e32 v0, 0x4f7ffffe, v0
	v_cvt_u32_f32_e32 v0, v0
	s_mul_i32 s8, s8, 3
	v_readfirstlane_b32 s20, v0
	s_mul_i32 s15, s15, s20
	s_mul_hi_u32 s15, s20, s15
	s_add_i32 s20, s20, s15
	s_mul_hi_u32 s15, s10, s20
	s_mul_i32 s20, s15, s13
	s_sub_i32 s10, s10, s20
	s_add_i32 s21, s15, 1
	s_sub_i32 s20, s10, s13
	s_cmp_ge_u32 s10, s13
	s_cselect_b32 s15, s21, s15
	s_cselect_b32 s10, s20, s10
	s_add_i32 s20, s15, 1
	s_cmp_ge_u32 s10, s13
	s_cselect_b32 s10, s20, s15
	s_xor_b32 s10, s10, s14
	s_sub_i32 s10, s10, s14
	s_mul_i32 s12, s10, s12
	s_sub_i32 s9, s9, s12
	s_add_i32 s8, s10, s8
	s_add_i32 s11, s11, s9
	s_mul_i32 s9, s8, 0x4ec5
	s_lshr_b32 s10, s9, 31
	s_ashr_i32 s9, s9, 19
	s_add_i32 s9, s9, s10
	s_mul_i32 s9, s9, 26
	s_sub_i32 s8, s8, s9
	s_sext_i32_i16 s37, s8
	s_lshl_b32 s22, s37, 8
	v_readfirstlane_b32 s8, v151
	s_ashr_i32 s23, s22, 31
	s_lshl_b32 s12, s11, 8
	s_lshl_b32 s13, s8, 10
	s_lshl_b64 s[8:9], s[22:23], 11
	s_add_u32 s10, s18, s8
	s_addc_u32 s11, s19, s9
	s_add_i32 s20, s13, 0
	s_ashr_i32 s13, s12, 31
	v_lshl_add_u64 v[2:3], s[10:11], 0, v[130:131]
	s_add_i32 s21, s20, 0x10000
	v_lshl_add_u64 v[4:5], s[10:11], 0, v[132:133]
	s_add_i32 s23, s20, 0x12000
	s_lshl_b64 s[10:11], s[12:13], 11
	s_add_u32 s14, s16, s10
	s_addc_u32 s15, s17, s11
	v_lshl_add_u64 v[8:9], s[14:15], 0, v[130:131]
	v_lshl_add_u64 v[6:7], s[14:15], 0, v[132:133]
	s_or_b32 s14, s22, 0x80
	s_ashr_i32 s15, s14, 31
	s_add_i32 s13, s20, 0x2000
	s_lshl_b64 s[14:15], s[14:15], 11
	s_add_u32 s14, s18, s14
	s_mov_b32 m0, s21
	s_addc_u32 s15, s19, s15
	global_load_lds_dwordx4 v[2:3], off
	s_mov_b32 m0, s23
	v_lshl_add_u64 v[12:13], s[14:15], 0, v[130:131]
	v_lshl_add_u64 v[10:11], s[14:15], 0, v[132:133]
	s_or_b32 s14, s12, 0x80
	global_load_lds_dwordx4 v[4:5], off
	s_mov_b32 m0, s20
	s_ashr_i32 s15, s14, 31
	global_load_lds_dwordx4 v[8:9], off
	s_mov_b32 m0, s13
	s_add_i32 s24, s20, 0x14000
	s_add_i32 s25, s20, 0x16000
	s_lshl_b64 s[14:15], s[14:15], 11
	global_load_lds_dwordx4 v[6:7], off
	s_mov_b32 m0, s24
	s_add_u32 s14, s16, s14
	global_load_lds_dwordx4 v[12:13], off
	s_mov_b32 m0, s25
	s_addc_u32 s15, s17, s15
	s_add_i32 s26, s20, 0x4000
	global_load_lds_dwordx4 v[10:11], off
	v_lshl_add_u64 v[142:143], s[14:15], 0, v[130:131]
	s_mov_b32 m0, s26
	s_add_i32 s27, s20, 0x6000
	global_load_lds_dwordx4 v[142:143], off
	v_lshl_add_u64 v[144:145], s[14:15], 0, v[132:133]
	s_mov_b32 m0, s27
	s_nop 0
	global_load_lds_dwordx4 v[144:145], off
	s_and_saveexec_b64 s[14:15], s[4:5]
	s_cbranch_execz .LBB0_448
	s_barrier
